# gate epilogue: bias add and -log2e scale fused into one v_fmamk per logit (bias pre-scaled once per pass)
# speedup vs baseline: 1.0010x; 1.0010x over previous
; DI float sigm(float x) { return 1.f / (1.f + __expf(-x)); }
; DI void gate_reg(PREF p, int l, int n, f32x4 (&acc)[2][2][4][2], int dt) {
;     ...
;       u32x4 bn[4], pv[4];
; #pragma unroll
;       for (int m = 0; m < 4; ++m) {
;         bn[m] = sbn[((ai * 2 + bj) * 4 + m) * 64];
;         if (n > 0) pv[m] = ssum[((ai * 2 + bj) * 4 + m) * 64];
;       }
; #pragma unroll
;       for (int m = 0; m < 4; ++m) {
;         float b[8]; unpack8(bn[m], b);
;         float v[8];
; #pragma unroll
;         for (int nn = 0; nn < 2; ++nn)
; #pragma unroll
;           for (int j = 0; j < 4; ++j) v[nn * 4 + j] = sigm(acc[ai][bj][m][nn][j] + bias[bj][nn]) * b[nn * 4 + j];
;         if (n > 0) {
;           float o[8]; unpack8(pv[m], o);
; #pragma unroll
;           for (int e = 0; e < 8; ++e) v[e] += o[e];
.LBB0_108:
	s_or_b64 exec, exec, s[8:9]
	s_lshl_b32 s0, s23, 8
	s_add_u32 s98, s25, s0
	s_addc_u32 s99, s48, 0
	s_lshr_b32 s0, s23, 1
	s_lshl_b32 s0, s0, 12
	s_add_u32 s8, s63, s0
	s_addc_u32 s9, s64, 0
	s_add_u32 s10, s8, 0x20000
	s_addc_u32 s11, s9, 0
	s_add_u32 s42, s8, 0x40000
	s_addc_u32 s43, s9, 0
	s_add_u32 s44, s8, 0x60000
	s_addc_u32 s45, s9, 0
	s_lshl_b32 s0, s23, 1
	v_bfe_u32 v155, v168, 6, 2
	v_lshlrev_b32_e32 v130, 6, v155
	v_and_b32_e32 v131, 15, v168
	v_lshl_or_b32 v130, v131, 2, v130
	v_add_u32_e32 v131, 0x1000, v130
	v_add_u32_e32 v131, 0x2000, v130
	v_add_u32_e32 v131, 0x3000, v130
	v_lshrrev_b32_e32 v130, 1, v155
	v_add_u32_e32 v130, s0, v130
	v_and_b32_e32 v130, 3, v130
	v_lshrrev_b32_e32 v131, 8, v168
	v_lshl_add_u32 v130, v131, 2, v130
	v_lshlrev_b32_e32 v130, 14, v130
	v_and_b32_e32 v131, 63, v168
	v_lshl_or_b32 v142, v131, 4, v130
	v_and_b32_e32 v131, 1, v155
	v_lshl_or_b32 v142, v131, 3, v142
	v_add_u32_e32 v0, 0x2000, v142
	global_load_dwordx2 v[198:199], v142, s[8:9] offset:2048
	global_load_dwordx2 v[200:201], v142, s[10:11] offset:2048
	global_load_dwordx2 v[202:203], v142, s[42:43] offset:2048
	global_load_dwordx2 v[204:205], v142, s[44:45] offset:2048
	global_load_dwordx2 v[206:207], v142, s[8:9] offset:3072
	global_load_dwordx2 v[208:209], v142, s[10:11] offset:3072
	global_load_dwordx2 v[210:211], v142, s[42:43] offset:3072
	global_load_dwordx2 v[212:213], v142, s[44:45] offset:3072
	global_load_dwordx2 v[214:215], v0, s[8:9] offset:0
	global_load_dwordx2 v[216:217], v0, s[10:11] offset:0
	global_load_dwordx2 v[218:219], v0, s[42:43] offset:0
	global_load_dwordx2 v[220:221], v0, s[44:45] offset:0
	global_load_dwordx2 v[222:223], v0, s[8:9] offset:1024
	global_load_dwordx2 v[224:225], v0, s[10:11] offset:1024
	global_load_dwordx2 v[226:227], v0, s[42:43] offset:1024
	global_load_dwordx2 v[228:229], v0, s[44:45] offset:1024
	global_load_dwordx2 v[182:183], v0, s[8:9] offset:2048
	global_load_dwordx2 v[184:185], v0, s[10:11] offset:2048
	global_load_dwordx2 v[186:187], v0, s[42:43] offset:2048
	global_load_dwordx2 v[188:189], v0, s[44:45] offset:2048
	global_load_dwordx2 v[190:191], v0, s[8:9] offset:3072
	global_load_dwordx2 v[192:193], v0, s[10:11] offset:3072
	global_load_dwordx2 v[194:195], v0, s[42:43] offset:3072
	global_load_dwordx2 v[196:197], v0, s[44:45] offset:3072
	s_waitcnt vmcnt(24)
	v_mul_f32_e32 v170, 0xbfb8aa3b, v170
	v_mul_f32_e32 v252, 0xbfb8aa3b, v252
	v_mul_f32_e32 v253, 0xbfb8aa3b, v253
	v_mul_f32_e32 v162, 0xbfb8aa3b, v162
	v_fmamk_f32 v158, v158, 0xbfb8aa3b, v170
	v_exp_f32_e32 v158, v158
	v_fmamk_f32 v159, v159, 0xbfb8aa3b, v170
	v_exp_f32_e32 v159, v159
	v_fmamk_f32 v160, v160, 0xbfb8aa3b, v170
	v_exp_f32_e32 v160, v160
	v_fmamk_f32 v161, v161, 0xbfb8aa3b, v170
	v_exp_f32_e32 v161, v161
	v_fmamk_f32 v150, v150, 0xbfb8aa3b, v252
	v_exp_f32_e32 v150, v150
	v_fmamk_f32 v151, v151, 0xbfb8aa3b, v252
	v_exp_f32_e32 v151, v151
	v_fmamk_f32 v152, v152, 0xbfb8aa3b, v252
	v_exp_f32_e32 v152, v152
	v_fmamk_f32 v153, v153, 0xbfb8aa3b, v252
	v_exp_f32_e32 v153, v153
	v_fmamk_f32 v110, v110, 0xbfb8aa3b, v253
	v_exp_f32_e32 v110, v110
	v_fmamk_f32 v111, v111, 0xbfb8aa3b, v253
	v_exp_f32_e32 v111, v111
	v_fmamk_f32 v112, v112, 0xbfb8aa3b, v253
	v_exp_f32_e32 v112, v112
	v_fmamk_f32 v113, v113, 0xbfb8aa3b, v253
	v_exp_f32_e32 v113, v113
	v_fmamk_f32 v106, v106, 0xbfb8aa3b, v162
	v_exp_f32_e32 v106, v106
	v_fmamk_f32 v107, v107, 0xbfb8aa3b, v162
	v_exp_f32_e32 v107, v107
	v_fmamk_f32 v108, v108, 0xbfb8aa3b, v162
	v_exp_f32_e32 v108, v108
	v_fmamk_f32 v109, v109, 0xbfb8aa3b, v162
	v_exp_f32_e32 v109, v109
	v_pk_add_f32 v[158:159], v[158:159], 1.0 op_sel_hi:[1,0]
	v_lshlrev_b32_e32 v156, 16, v230
	v_and_b32_e32 v157, 0xffff0000, v230
	v_rcp_f32_e32 v158, v158
	v_rcp_f32_e32 v159, v159
	v_pk_add_f32 v[160:161], v[160:161], 1.0 op_sel_hi:[1,0]
	v_lshlrev_b32_e32 v164, 16, v231
	v_and_b32_e32 v165, 0xffff0000, v231
	v_rcp_f32_e32 v160, v160
	v_rcp_f32_e32 v161, v161
	v_pk_mul_f32 v[158:159], v[158:159], v[156:157]
	v_pk_mul_f32 v[160:161], v[160:161], v[164:165]
	v_pk_add_f32 v[150:151], v[150:151], 1.0 op_sel_hi:[1,0]
	v_lshlrev_b32_e32 v156, 16, v232
	v_and_b32_e32 v157, 0xffff0000, v232
	v_rcp_f32_e32 v150, v150
	v_rcp_f32_e32 v151, v151
	v_pk_add_f32 v[152:153], v[152:153], 1.0 op_sel_hi:[1,0]
	v_lshlrev_b32_e32 v164, 16, v233
	v_and_b32_e32 v165, 0xffff0000, v233
	v_rcp_f32_e32 v152, v152
	v_rcp_f32_e32 v153, v153
	v_pk_fma_f32 v[158:159], v[150:151], v[156:157], v[158:159]
	v_pk_fma_f32 v[160:161], v[152:153], v[164:165], v[160:161]
	v_pk_add_f32 v[110:111], v[110:111], 1.0 op_sel_hi:[1,0]
	v_lshlrev_b32_e32 v156, 16, v234
	v_and_b32_e32 v157, 0xffff0000, v234
	v_rcp_f32_e32 v110, v110
	v_rcp_f32_e32 v111, v111
	v_pk_add_f32 v[112:113], v[112:113], 1.0 op_sel_hi:[1,0]
	v_lshlrev_b32_e32 v164, 16, v235
	v_and_b32_e32 v165, 0xffff0000, v235
	v_rcp_f32_e32 v112, v112
	v_rcp_f32_e32 v113, v113
	v_pk_fma_f32 v[158:159], v[110:111], v[156:157], v[158:159]
	v_pk_fma_f32 v[160:161], v[112:113], v[164:165], v[160:161]
	v_pk_add_f32 v[106:107], v[106:107], 1.0 op_sel_hi:[1,0]
	v_lshlrev_b32_e32 v156, 16, v236
	v_and_b32_e32 v157, 0xffff0000, v236
	v_rcp_f32_e32 v106, v106
	v_rcp_f32_e32 v107, v107
	v_pk_add_f32 v[108:109], v[108:109], 1.0 op_sel_hi:[1,0]
	v_lshlrev_b32_e32 v164, 16, v237
	v_and_b32_e32 v165, 0xffff0000, v237
	v_rcp_f32_e32 v108, v108
	v_rcp_f32_e32 v109, v109
	v_pk_fma_f32 v[158:159], v[106:107], v[156:157], v[158:159]
	v_pk_fma_f32 v[160:161], v[108:109], v[164:165], v[160:161]
	s_waitcnt vmcnt(24)
; DI float sigm(float x) { return 1.f / (1.f + __expf(-x)); }
; DI void gate_reg(PREF p, int l, int n, f32x4 (&acc)[2][2][4][2], int dt) {
;     ...
; #pragma unroll
;       for (int m = 0; m < 4; ++m) {
;         float b[8]; unpack8(bn[m], b);
;         float v[8];
; #pragma unroll
;         for (int nn = 0; nn < 2; ++nn)
; #pragma unroll
;           for (int j = 0; j < 4; ++j) v[nn * 4 + j] = sigm(acc[ai][bj][m][nn][j] + bias[bj][nn]) * b[nn * 4 + j];
;         if (n > 0) {
;           float o[8]; unpack8(pv[m], o);
; #pragma unroll
;           for (int e = 0; e < 8; ++e) v[e] += o[e];
	v_fmamk_f32 v146, v146, 0xbfb8aa3b, v170
	v_exp_f32_e32 v146, v146
	v_fmamk_f32 v147, v147, 0xbfb8aa3b, v170
	v_exp_f32_e32 v147, v147
	v_fmamk_f32 v148, v148, 0xbfb8aa3b, v170
	v_exp_f32_e32 v148, v148
	v_fmamk_f32 v149, v149, 0xbfb8aa3b, v170
	v_exp_f32_e32 v149, v149
	v_fmamk_f32 v138, v138, 0xbfb8aa3b, v252
	v_exp_f32_e32 v138, v138
	v_fmamk_f32 v139, v139, 0xbfb8aa3b, v252
	v_exp_f32_e32 v139, v139
	v_fmamk_f32 v140, v140, 0xbfb8aa3b, v252
	v_exp_f32_e32 v140, v140
	v_fmamk_f32 v141, v141, 0xbfb8aa3b, v252
	v_exp_f32_e32 v141, v141
	v_fmamk_f32 v102, v102, 0xbfb8aa3b, v253
	v_exp_f32_e32 v102, v102
	v_fmamk_f32 v103, v103, 0xbfb8aa3b, v253
	v_exp_f32_e32 v103, v103
	v_fmamk_f32 v104, v104, 0xbfb8aa3b, v253
	v_exp_f32_e32 v104, v104
	v_fmamk_f32 v105, v105, 0xbfb8aa3b, v253
	v_exp_f32_e32 v105, v105
	v_fmamk_f32 v98, v98, 0xbfb8aa3b, v162
	v_exp_f32_e32 v98, v98
	v_fmamk_f32 v99, v99, 0xbfb8aa3b, v162
	v_exp_f32_e32 v99, v99
	v_fmamk_f32 v100, v100, 0xbfb8aa3b, v162
	v_exp_f32_e32 v100, v100
	v_fmamk_f32 v101, v101, 0xbfb8aa3b, v162
	v_exp_f32_e32 v101, v101
	v_pk_add_f32 v[146:147], v[146:147], 1.0 op_sel_hi:[1,0]
	v_lshlrev_b32_e32 v156, 16, v238
	v_and_b32_e32 v157, 0xffff0000, v238
	v_rcp_f32_e32 v146, v146
	v_rcp_f32_e32 v147, v147
	v_pk_add_f32 v[148:149], v[148:149], 1.0 op_sel_hi:[1,0]
	v_lshlrev_b32_e32 v164, 16, v239
	v_and_b32_e32 v165, 0xffff0000, v239
	v_rcp_f32_e32 v148, v148
	v_rcp_f32_e32 v149, v149
	v_pk_mul_f32 v[146:147], v[146:147], v[156:157]
	v_pk_mul_f32 v[148:149], v[148:149], v[164:165]
	v_pk_add_f32 v[138:139], v[138:139], 1.0 op_sel_hi:[1,0]
	v_lshlrev_b32_e32 v156, 16, v240
	v_and_b32_e32 v157, 0xffff0000, v240
	v_rcp_f32_e32 v138, v138
	v_rcp_f32_e32 v139, v139
	v_pk_add_f32 v[140:141], v[140:141], 1.0 op_sel_hi:[1,0]
	v_lshlrev_b32_e32 v164, 16, v241
	v_and_b32_e32 v165, 0xffff0000, v241
	v_rcp_f32_e32 v140, v140
	v_rcp_f32_e32 v141, v141
	v_pk_fma_f32 v[146:147], v[138:139], v[156:157], v[146:147]
	v_pk_fma_f32 v[148:149], v[140:141], v[164:165], v[148:149]
	v_pk_add_f32 v[102:103], v[102:103], 1.0 op_sel_hi:[1,0]
	v_lshlrev_b32_e32 v156, 16, v242
	v_and_b32_e32 v157, 0xffff0000, v242
	v_rcp_f32_e32 v102, v102
	v_rcp_f32_e32 v103, v103
	v_pk_add_f32 v[104:105], v[104:105], 1.0 op_sel_hi:[1,0]
	v_lshlrev_b32_e32 v164, 16, v243
	v_and_b32_e32 v165, 0xffff0000, v243
	v_rcp_f32_e32 v104, v104
	v_rcp_f32_e32 v105, v105
	v_pk_fma_f32 v[146:147], v[102:103], v[156:157], v[146:147]
	v_pk_fma_f32 v[148:149], v[104:105], v[164:165], v[148:149]
	v_pk_add_f32 v[98:99], v[98:99], 1.0 op_sel_hi:[1,0]
	v_lshlrev_b32_e32 v156, 16, v244
	v_and_b32_e32 v157, 0xffff0000, v244
	v_rcp_f32_e32 v98, v98
	v_rcp_f32_e32 v99, v99
	v_pk_add_f32 v[100:101], v[100:101], 1.0 op_sel_hi:[1,0]
	v_lshlrev_b32_e32 v164, 16, v245
	v_and_b32_e32 v165, 0xffff0000, v245
	v_rcp_f32_e32 v100, v100
	v_rcp_f32_e32 v101, v101
	v_pk_fma_f32 v[146:147], v[98:99], v[156:157], v[146:147]
	v_pk_fma_f32 v[148:149], v[100:101], v[164:165], v[148:149]
	s_waitcnt vmcnt(20)
	v_fmamk_f32 v134, v134, 0xbfb8aa3b, v170
	v_exp_f32_e32 v134, v134
	v_fmamk_f32 v135, v135, 0xbfb8aa3b, v170
	v_exp_f32_e32 v135, v135
	v_fmamk_f32 v136, v136, 0xbfb8aa3b, v170
	v_exp_f32_e32 v136, v136
	v_fmamk_f32 v137, v137, 0xbfb8aa3b, v170
	v_exp_f32_e32 v137, v137
	v_fmamk_f32 v126, v126, 0xbfb8aa3b, v252
	v_exp_f32_e32 v126, v126
	v_fmamk_f32 v127, v127, 0xbfb8aa3b, v252
	v_exp_f32_e32 v127, v127
	v_fmamk_f32 v128, v128, 0xbfb8aa3b, v252
	v_exp_f32_e32 v128, v128
	v_fmamk_f32 v129, v129, 0xbfb8aa3b, v252
	v_exp_f32_e32 v129, v129
	v_fmamk_f32 v94, v94, 0xbfb8aa3b, v253
	v_exp_f32_e32 v94, v94
	v_fmamk_f32 v95, v95, 0xbfb8aa3b, v253
	v_exp_f32_e32 v95, v95
	v_fmamk_f32 v96, v96, 0xbfb8aa3b, v253
	v_exp_f32_e32 v96, v96
	v_fmamk_f32 v97, v97, 0xbfb8aa3b, v253
	v_exp_f32_e32 v97, v97
	v_fmamk_f32 v90, v90, 0xbfb8aa3b, v162
	v_exp_f32_e32 v90, v90
	v_fmamk_f32 v91, v91, 0xbfb8aa3b, v162
	v_exp_f32_e32 v91, v91
	v_fmamk_f32 v92, v92, 0xbfb8aa3b, v162
	v_exp_f32_e32 v92, v92
	v_fmamk_f32 v93, v93, 0xbfb8aa3b, v162
	v_exp_f32_e32 v93, v93
	v_pk_add_f32 v[134:135], v[134:135], 1.0 op_sel_hi:[1,0]
	v_lshlrev_b32_e32 v156, 16, v198
	v_and_b32_e32 v157, 0xffff0000, v198
	v_rcp_f32_e32 v134, v134
	v_rcp_f32_e32 v135, v135
	v_pk_add_f32 v[136:137], v[136:137], 1.0 op_sel_hi:[1,0]
	v_lshlrev_b32_e32 v164, 16, v199
	v_and_b32_e32 v165, 0xffff0000, v199
	v_rcp_f32_e32 v136, v136
	v_rcp_f32_e32 v137, v137
	v_pk_mul_f32 v[134:135], v[134:135], v[156:157]
	v_pk_mul_f32 v[136:137], v[136:137], v[164:165]
	v_pk_add_f32 v[126:127], v[126:127], 1.0 op_sel_hi:[1,0]
	v_lshlrev_b32_e32 v156, 16, v200
	v_and_b32_e32 v157, 0xffff0000, v200
	v_rcp_f32_e32 v126, v126
	v_rcp_f32_e32 v127, v127
	v_pk_add_f32 v[128:129], v[128:129], 1.0 op_sel_hi:[1,0]
	v_lshlrev_b32_e32 v164, 16, v201
	v_and_b32_e32 v165, 0xffff0000, v201
	v_rcp_f32_e32 v128, v128
	v_rcp_f32_e32 v129, v129
	v_pk_fma_f32 v[134:135], v[126:127], v[156:157], v[134:135]
	v_pk_fma_f32 v[136:137], v[128:129], v[164:165], v[136:137]
	v_pk_add_f32 v[94:95], v[94:95], 1.0 op_sel_hi:[1,0]
	v_lshlrev_b32_e32 v156, 16, v202
	v_and_b32_e32 v157, 0xffff0000, v202
	v_rcp_f32_e32 v94, v94
	v_rcp_f32_e32 v95, v95
	v_pk_add_f32 v[96:97], v[96:97], 1.0 op_sel_hi:[1,0]
	v_lshlrev_b32_e32 v164, 16, v203
	v_and_b32_e32 v165, 0xffff0000, v203
	v_rcp_f32_e32 v96, v96
	v_rcp_f32_e32 v97, v97
	v_pk_fma_f32 v[134:135], v[94:95], v[156:157], v[134:135]
	v_pk_fma_f32 v[136:137], v[96:97], v[164:165], v[136:137]
	v_pk_add_f32 v[90:91], v[90:91], 1.0 op_sel_hi:[1,0]
	v_lshlrev_b32_e32 v156, 16, v204
	v_and_b32_e32 v157, 0xffff0000, v204
	v_rcp_f32_e32 v90, v90
	v_rcp_f32_e32 v91, v91
	v_pk_add_f32 v[92:93], v[92:93], 1.0 op_sel_hi:[1,0]
	v_lshlrev_b32_e32 v164, 16, v205
	v_and_b32_e32 v165, 0xffff0000, v205
	v_rcp_f32_e32 v92, v92
	v_rcp_f32_e32 v93, v93
	v_pk_fma_f32 v[134:135], v[90:91], v[156:157], v[134:135]
	v_pk_fma_f32 v[136:137], v[92:93], v[164:165], v[136:137]
	s_waitcnt vmcnt(16)
; DI float sigm(float x) { return 1.f / (1.f + __expf(-x)); }
; DI void gate_reg(PREF p, int l, int n, f32x4 (&acc)[2][2][4][2], int dt) {
;     ...
; #pragma unroll
;       for (int m = 0; m < 4; ++m) {
;         float b[8]; unpack8(bn[m], b);
;         float v[8];
; #pragma unroll
;         for (int nn = 0; nn < 2; ++nn)
; #pragma unroll
;           for (int j = 0; j < 4; ++j) v[nn * 4 + j] = sigm(acc[ai][bj][m][nn][j] + bias[bj][nn]) * b[nn * 4 + j];
;         if (n > 0) {
;           float o[8]; unpack8(pv[m], o);
; #pragma unroll
;           for (int e = 0; e < 8; ++e) v[e] += o[e];
	v_fmamk_f32 v122, v122, 0xbfb8aa3b, v170
	v_exp_f32_e32 v122, v122
	v_fmamk_f32 v123, v123, 0xbfb8aa3b, v170
	v_exp_f32_e32 v123, v123
	v_fmamk_f32 v124, v124, 0xbfb8aa3b, v170
	v_exp_f32_e32 v124, v124
	v_fmamk_f32 v125, v125, 0xbfb8aa3b, v170
	v_exp_f32_e32 v125, v125
	v_fmamk_f32 v114, v114, 0xbfb8aa3b, v252
	v_exp_f32_e32 v114, v114
	v_fmamk_f32 v115, v115, 0xbfb8aa3b, v252
	v_exp_f32_e32 v115, v115
	v_fmamk_f32 v116, v116, 0xbfb8aa3b, v252
	v_exp_f32_e32 v116, v116
	v_fmamk_f32 v117, v117, 0xbfb8aa3b, v252
	v_exp_f32_e32 v117, v117
	v_fmamk_f32 v86, v86, 0xbfb8aa3b, v253
	v_exp_f32_e32 v86, v86
	v_fmamk_f32 v87, v87, 0xbfb8aa3b, v253
	v_exp_f32_e32 v87, v87
	v_fmamk_f32 v88, v88, 0xbfb8aa3b, v253
	v_exp_f32_e32 v88, v88
	v_fmamk_f32 v89, v89, 0xbfb8aa3b, v253
	v_exp_f32_e32 v89, v89
	v_fmamk_f32 v82, v82, 0xbfb8aa3b, v162
	v_exp_f32_e32 v82, v82
	v_fmamk_f32 v83, v83, 0xbfb8aa3b, v162
	v_exp_f32_e32 v83, v83
	v_fmamk_f32 v84, v84, 0xbfb8aa3b, v162
	v_exp_f32_e32 v84, v84
	v_fmamk_f32 v85, v85, 0xbfb8aa3b, v162
	v_exp_f32_e32 v85, v85
	v_pk_add_f32 v[122:123], v[122:123], 1.0 op_sel_hi:[1,0]
	v_lshlrev_b32_e32 v156, 16, v206
	v_and_b32_e32 v157, 0xffff0000, v206
	v_rcp_f32_e32 v122, v122
	v_rcp_f32_e32 v123, v123
	v_pk_add_f32 v[124:125], v[124:125], 1.0 op_sel_hi:[1,0]
	v_lshlrev_b32_e32 v164, 16, v207
	v_and_b32_e32 v165, 0xffff0000, v207
	v_rcp_f32_e32 v124, v124
	v_rcp_f32_e32 v125, v125
	v_pk_mul_f32 v[122:123], v[122:123], v[156:157]
	v_pk_mul_f32 v[124:125], v[124:125], v[164:165]
	v_pk_add_f32 v[114:115], v[114:115], 1.0 op_sel_hi:[1,0]
	v_lshlrev_b32_e32 v156, 16, v208
	v_and_b32_e32 v157, 0xffff0000, v208
	v_rcp_f32_e32 v114, v114
	v_rcp_f32_e32 v115, v115
	v_pk_add_f32 v[116:117], v[116:117], 1.0 op_sel_hi:[1,0]
	v_lshlrev_b32_e32 v164, 16, v209
	v_and_b32_e32 v165, 0xffff0000, v209
	v_rcp_f32_e32 v116, v116
	v_rcp_f32_e32 v117, v117
	v_pk_fma_f32 v[122:123], v[114:115], v[156:157], v[122:123]
	v_pk_fma_f32 v[124:125], v[116:117], v[164:165], v[124:125]
	v_pk_add_f32 v[86:87], v[86:87], 1.0 op_sel_hi:[1,0]
	v_lshlrev_b32_e32 v156, 16, v210
	v_and_b32_e32 v157, 0xffff0000, v210
	v_rcp_f32_e32 v86, v86
	v_rcp_f32_e32 v87, v87
	v_pk_add_f32 v[88:89], v[88:89], 1.0 op_sel_hi:[1,0]
	v_lshlrev_b32_e32 v164, 16, v211
	v_and_b32_e32 v165, 0xffff0000, v211
	v_rcp_f32_e32 v88, v88
	v_rcp_f32_e32 v89, v89
	v_pk_fma_f32 v[122:123], v[86:87], v[156:157], v[122:123]
	v_pk_fma_f32 v[124:125], v[88:89], v[164:165], v[124:125]
	v_pk_add_f32 v[82:83], v[82:83], 1.0 op_sel_hi:[1,0]
	v_lshlrev_b32_e32 v156, 16, v212
	v_and_b32_e32 v157, 0xffff0000, v212
	v_rcp_f32_e32 v82, v82
	v_rcp_f32_e32 v83, v83
	v_pk_add_f32 v[84:85], v[84:85], 1.0 op_sel_hi:[1,0]
	v_lshlrev_b32_e32 v164, 16, v213
	v_and_b32_e32 v165, 0xffff0000, v213
	v_rcp_f32_e32 v84, v84
	v_rcp_f32_e32 v85, v85
	v_pk_fma_f32 v[122:123], v[82:83], v[156:157], v[122:123]
	v_pk_fma_f32 v[124:125], v[84:85], v[164:165], v[124:125]
	s_waitcnt vmcnt(12)
	v_fmamk_f32 v78, v78, 0xbfb8aa3b, v170
	v_exp_f32_e32 v78, v78
	v_fmamk_f32 v79, v79, 0xbfb8aa3b, v170
	v_exp_f32_e32 v79, v79
	v_fmamk_f32 v80, v80, 0xbfb8aa3b, v170
	v_exp_f32_e32 v80, v80
	v_fmamk_f32 v81, v81, 0xbfb8aa3b, v170
	v_exp_f32_e32 v81, v81
	v_fmamk_f32 v74, v74, 0xbfb8aa3b, v252
	v_exp_f32_e32 v74, v74
	v_fmamk_f32 v75, v75, 0xbfb8aa3b, v252
	v_exp_f32_e32 v75, v75
	v_fmamk_f32 v76, v76, 0xbfb8aa3b, v252
	v_exp_f32_e32 v76, v76
	v_fmamk_f32 v77, v77, 0xbfb8aa3b, v252
	v_exp_f32_e32 v77, v77
	v_fmamk_f32 v46, v46, 0xbfb8aa3b, v253
	v_exp_f32_e32 v46, v46
	v_fmamk_f32 v47, v47, 0xbfb8aa3b, v253
	v_exp_f32_e32 v47, v47
	v_fmamk_f32 v48, v48, 0xbfb8aa3b, v253
	v_exp_f32_e32 v48, v48
	v_fmamk_f32 v49, v49, 0xbfb8aa3b, v253
	v_exp_f32_e32 v49, v49
	v_fmamk_f32 v38, v38, 0xbfb8aa3b, v162
	v_exp_f32_e32 v38, v38
	v_fmamk_f32 v39, v39, 0xbfb8aa3b, v162
	v_exp_f32_e32 v39, v39
	v_fmamk_f32 v40, v40, 0xbfb8aa3b, v162
	v_exp_f32_e32 v40, v40
	v_fmamk_f32 v41, v41, 0xbfb8aa3b, v162
	v_exp_f32_e32 v41, v41
	v_pk_add_f32 v[78:79], v[78:79], 1.0 op_sel_hi:[1,0]
	v_lshlrev_b32_e32 v156, 16, v214
	v_and_b32_e32 v157, 0xffff0000, v214
	v_rcp_f32_e32 v78, v78
	v_rcp_f32_e32 v79, v79
	v_pk_add_f32 v[80:81], v[80:81], 1.0 op_sel_hi:[1,0]
	v_lshlrev_b32_e32 v164, 16, v215
	v_and_b32_e32 v165, 0xffff0000, v215
	v_rcp_f32_e32 v80, v80
	v_rcp_f32_e32 v81, v81
	v_pk_mul_f32 v[78:79], v[78:79], v[156:157]
	v_pk_mul_f32 v[80:81], v[80:81], v[164:165]
	v_pk_add_f32 v[74:75], v[74:75], 1.0 op_sel_hi:[1,0]
	v_lshlrev_b32_e32 v156, 16, v216
	v_and_b32_e32 v157, 0xffff0000, v216
	v_rcp_f32_e32 v74, v74
	v_rcp_f32_e32 v75, v75
	v_pk_add_f32 v[76:77], v[76:77], 1.0 op_sel_hi:[1,0]
	v_lshlrev_b32_e32 v164, 16, v217
	v_and_b32_e32 v165, 0xffff0000, v217
	v_rcp_f32_e32 v76, v76
	v_rcp_f32_e32 v77, v77
	v_pk_fma_f32 v[78:79], v[74:75], v[156:157], v[78:79]
	v_pk_fma_f32 v[80:81], v[76:77], v[164:165], v[80:81]
	v_pk_add_f32 v[46:47], v[46:47], 1.0 op_sel_hi:[1,0]
	v_lshlrev_b32_e32 v156, 16, v218
	v_and_b32_e32 v157, 0xffff0000, v218
	v_rcp_f32_e32 v46, v46
	v_rcp_f32_e32 v47, v47
	v_pk_add_f32 v[48:49], v[48:49], 1.0 op_sel_hi:[1,0]
	v_lshlrev_b32_e32 v164, 16, v219
	v_and_b32_e32 v165, 0xffff0000, v219
	v_rcp_f32_e32 v48, v48
	v_rcp_f32_e32 v49, v49
	v_pk_fma_f32 v[78:79], v[46:47], v[156:157], v[78:79]
	v_pk_fma_f32 v[80:81], v[48:49], v[164:165], v[80:81]
	v_pk_add_f32 v[38:39], v[38:39], 1.0 op_sel_hi:[1,0]
	v_lshlrev_b32_e32 v156, 16, v220
	v_and_b32_e32 v157, 0xffff0000, v220
	v_rcp_f32_e32 v38, v38
	v_rcp_f32_e32 v39, v39
	v_pk_add_f32 v[40:41], v[40:41], 1.0 op_sel_hi:[1,0]
	v_lshlrev_b32_e32 v164, 16, v221
	v_and_b32_e32 v165, 0xffff0000, v221
	v_rcp_f32_e32 v40, v40
	v_rcp_f32_e32 v41, v41
	v_pk_fma_f32 v[78:79], v[38:39], v[156:157], v[78:79]
	v_pk_fma_f32 v[80:81], v[40:41], v[164:165], v[80:81]
	s_waitcnt vmcnt(8)
; DI float sigm(float x) { return 1.f / (1.f + __expf(-x)); }
; DI void gate_reg(PREF p, int l, int n, f32x4 (&acc)[2][2][4][2], int dt) {
;     ...
; #pragma unroll
;       for (int m = 0; m < 4; ++m) {
;         float b[8]; unpack8(bn[m], b);
;         float v[8];
; #pragma unroll
;         for (int nn = 0; nn < 2; ++nn)
; #pragma unroll
;           for (int j = 0; j < 4; ++j) v[nn * 4 + j] = sigm(acc[ai][bj][m][nn][j] + bias[bj][nn]) * b[nn * 4 + j];
;         if (n > 0) {
;           float o[8]; unpack8(pv[m], o);
; #pragma unroll
;           for (int e = 0; e < 8; ++e) v[e] += o[e];
	v_fmamk_f32 v70, v70, 0xbfb8aa3b, v170
	v_exp_f32_e32 v70, v70
	v_fmamk_f32 v71, v71, 0xbfb8aa3b, v170
	v_exp_f32_e32 v71, v71
	v_fmamk_f32 v72, v72, 0xbfb8aa3b, v170
	v_exp_f32_e32 v72, v72
	v_fmamk_f32 v73, v73, 0xbfb8aa3b, v170
	v_exp_f32_e32 v73, v73
	v_fmamk_f32 v66, v66, 0xbfb8aa3b, v252
	v_exp_f32_e32 v66, v66
	v_fmamk_f32 v67, v67, 0xbfb8aa3b, v252
	v_exp_f32_e32 v67, v67
	v_fmamk_f32 v68, v68, 0xbfb8aa3b, v252
	v_exp_f32_e32 v68, v68
	v_fmamk_f32 v69, v69, 0xbfb8aa3b, v252
	v_exp_f32_e32 v69, v69
	v_fmamk_f32 v34, v34, 0xbfb8aa3b, v253
	v_exp_f32_e32 v34, v34
	v_fmamk_f32 v35, v35, 0xbfb8aa3b, v253
	v_exp_f32_e32 v35, v35
	v_fmamk_f32 v36, v36, 0xbfb8aa3b, v253
	v_exp_f32_e32 v36, v36
	v_fmamk_f32 v37, v37, 0xbfb8aa3b, v253
	v_exp_f32_e32 v37, v37
	v_fmamk_f32 v26, v26, 0xbfb8aa3b, v162
	v_exp_f32_e32 v26, v26
	v_fmamk_f32 v27, v27, 0xbfb8aa3b, v162
	v_exp_f32_e32 v27, v27
	v_fmamk_f32 v28, v28, 0xbfb8aa3b, v162
	v_exp_f32_e32 v28, v28
	v_fmamk_f32 v29, v29, 0xbfb8aa3b, v162
	v_exp_f32_e32 v29, v29
	v_pk_add_f32 v[70:71], v[70:71], 1.0 op_sel_hi:[1,0]
	v_lshlrev_b32_e32 v156, 16, v222
	v_and_b32_e32 v157, 0xffff0000, v222
	v_rcp_f32_e32 v70, v70
	v_rcp_f32_e32 v71, v71
	v_pk_add_f32 v[72:73], v[72:73], 1.0 op_sel_hi:[1,0]
	v_lshlrev_b32_e32 v164, 16, v223
	v_and_b32_e32 v165, 0xffff0000, v223
	v_rcp_f32_e32 v72, v72
	v_rcp_f32_e32 v73, v73
	v_pk_mul_f32 v[70:71], v[70:71], v[156:157]
	v_pk_mul_f32 v[72:73], v[72:73], v[164:165]
	v_pk_add_f32 v[66:67], v[66:67], 1.0 op_sel_hi:[1,0]
	v_lshlrev_b32_e32 v156, 16, v224
	v_and_b32_e32 v157, 0xffff0000, v224
	v_rcp_f32_e32 v66, v66
	v_rcp_f32_e32 v67, v67
	v_pk_add_f32 v[68:69], v[68:69], 1.0 op_sel_hi:[1,0]
	v_lshlrev_b32_e32 v164, 16, v225
	v_and_b32_e32 v165, 0xffff0000, v225
	v_rcp_f32_e32 v68, v68
	v_rcp_f32_e32 v69, v69
	v_pk_fma_f32 v[70:71], v[66:67], v[156:157], v[70:71]
	v_pk_fma_f32 v[72:73], v[68:69], v[164:165], v[72:73]
	v_pk_add_f32 v[34:35], v[34:35], 1.0 op_sel_hi:[1,0]
	v_lshlrev_b32_e32 v156, 16, v226
	v_and_b32_e32 v157, 0xffff0000, v226
	v_rcp_f32_e32 v34, v34
	v_rcp_f32_e32 v35, v35
	v_pk_add_f32 v[36:37], v[36:37], 1.0 op_sel_hi:[1,0]
	v_lshlrev_b32_e32 v164, 16, v227
	v_and_b32_e32 v165, 0xffff0000, v227
	v_rcp_f32_e32 v36, v36
	v_rcp_f32_e32 v37, v37
	v_pk_fma_f32 v[70:71], v[34:35], v[156:157], v[70:71]
	v_pk_fma_f32 v[72:73], v[36:37], v[164:165], v[72:73]
	v_pk_add_f32 v[26:27], v[26:27], 1.0 op_sel_hi:[1,0]
	v_lshlrev_b32_e32 v156, 16, v228
	v_and_b32_e32 v157, 0xffff0000, v228
	v_rcp_f32_e32 v26, v26
	v_rcp_f32_e32 v27, v27
	v_pk_add_f32 v[28:29], v[28:29], 1.0 op_sel_hi:[1,0]
	v_lshlrev_b32_e32 v164, 16, v229
	v_and_b32_e32 v165, 0xffff0000, v229
	v_rcp_f32_e32 v28, v28
	v_rcp_f32_e32 v29, v29
	v_pk_fma_f32 v[70:71], v[26:27], v[156:157], v[70:71]
	v_pk_fma_f32 v[72:73], v[28:29], v[164:165], v[72:73]
	s_waitcnt vmcnt(4)
	v_fmamk_f32 v62, v62, 0xbfb8aa3b, v170
	v_exp_f32_e32 v62, v62
	v_fmamk_f32 v63, v63, 0xbfb8aa3b, v170
	v_exp_f32_e32 v63, v63
	v_fmamk_f32 v64, v64, 0xbfb8aa3b, v170
	v_exp_f32_e32 v64, v64
	v_fmamk_f32 v65, v65, 0xbfb8aa3b, v170
	v_exp_f32_e32 v65, v65
	v_fmamk_f32 v58, v58, 0xbfb8aa3b, v252
	v_exp_f32_e32 v58, v58
	v_fmamk_f32 v59, v59, 0xbfb8aa3b, v252
	v_exp_f32_e32 v59, v59
	v_fmamk_f32 v60, v60, 0xbfb8aa3b, v252
	v_exp_f32_e32 v60, v60
	v_fmamk_f32 v61, v61, 0xbfb8aa3b, v252
	v_exp_f32_e32 v61, v61
	v_fmamk_f32 v22, v22, 0xbfb8aa3b, v253
	v_exp_f32_e32 v22, v22
	v_fmamk_f32 v23, v23, 0xbfb8aa3b, v253
	v_exp_f32_e32 v23, v23
	v_fmamk_f32 v24, v24, 0xbfb8aa3b, v253
	v_exp_f32_e32 v24, v24
	v_fmamk_f32 v25, v25, 0xbfb8aa3b, v253
	v_exp_f32_e32 v25, v25
	v_fmamk_f32 v14, v14, 0xbfb8aa3b, v162
	v_exp_f32_e32 v14, v14
	v_fmamk_f32 v15, v15, 0xbfb8aa3b, v162
	v_exp_f32_e32 v15, v15
	v_fmamk_f32 v16, v16, 0xbfb8aa3b, v162
	v_exp_f32_e32 v16, v16
	v_fmamk_f32 v17, v17, 0xbfb8aa3b, v162
	v_exp_f32_e32 v17, v17
	v_pk_add_f32 v[62:63], v[62:63], 1.0 op_sel_hi:[1,0]
	v_lshlrev_b32_e32 v156, 16, v182
	v_and_b32_e32 v157, 0xffff0000, v182
	v_rcp_f32_e32 v62, v62
	v_rcp_f32_e32 v63, v63
	v_pk_add_f32 v[64:65], v[64:65], 1.0 op_sel_hi:[1,0]
	v_lshlrev_b32_e32 v164, 16, v183
	v_and_b32_e32 v165, 0xffff0000, v183
	v_rcp_f32_e32 v64, v64
	v_rcp_f32_e32 v65, v65
	v_pk_mul_f32 v[62:63], v[62:63], v[156:157]
	v_pk_mul_f32 v[64:65], v[64:65], v[164:165]
	v_pk_add_f32 v[58:59], v[58:59], 1.0 op_sel_hi:[1,0]
	v_lshlrev_b32_e32 v156, 16, v184
	v_and_b32_e32 v157, 0xffff0000, v184
	v_rcp_f32_e32 v58, v58
	v_rcp_f32_e32 v59, v59
	v_pk_add_f32 v[60:61], v[60:61], 1.0 op_sel_hi:[1,0]
	v_lshlrev_b32_e32 v164, 16, v185
	v_and_b32_e32 v165, 0xffff0000, v185
	v_rcp_f32_e32 v60, v60
	v_rcp_f32_e32 v61, v61
	v_pk_fma_f32 v[62:63], v[58:59], v[156:157], v[62:63]
	v_pk_fma_f32 v[64:65], v[60:61], v[164:165], v[64:65]
	v_pk_add_f32 v[22:23], v[22:23], 1.0 op_sel_hi:[1,0]
	v_lshlrev_b32_e32 v156, 16, v186
	v_and_b32_e32 v157, 0xffff0000, v186
	v_rcp_f32_e32 v22, v22
	v_rcp_f32_e32 v23, v23
	v_pk_add_f32 v[24:25], v[24:25], 1.0 op_sel_hi:[1,0]
	v_lshlrev_b32_e32 v164, 16, v187
	v_and_b32_e32 v165, 0xffff0000, v187
	v_rcp_f32_e32 v24, v24
	v_rcp_f32_e32 v25, v25
	v_pk_fma_f32 v[62:63], v[22:23], v[156:157], v[62:63]
	v_pk_fma_f32 v[64:65], v[24:25], v[164:165], v[64:65]
	v_pk_add_f32 v[14:15], v[14:15], 1.0 op_sel_hi:[1,0]
	v_lshlrev_b32_e32 v156, 16, v188
	v_and_b32_e32 v157, 0xffff0000, v188
	v_rcp_f32_e32 v14, v14
	v_rcp_f32_e32 v15, v15
	v_pk_add_f32 v[16:17], v[16:17], 1.0 op_sel_hi:[1,0]
	v_lshlrev_b32_e32 v164, 16, v189
	v_and_b32_e32 v165, 0xffff0000, v189
	v_rcp_f32_e32 v16, v16
	v_rcp_f32_e32 v17, v17
	v_pk_fma_f32 v[62:63], v[14:15], v[156:157], v[62:63]
	v_pk_fma_f32 v[64:65], v[16:17], v[164:165], v[64:65]
	s_waitcnt vmcnt(0)
; DI float sigm(float x) { return 1.f / (1.f + __expf(-x)); }
; DI u32x4 pack8(const float* f) { u32x4 o; o.x = pack2(f[0], f[1]); o.y = pack2(f[2], f[3]); o.z = pack2(f[4], f[5]); o.w = pack2(f[6], f[7]); return o; }
; DI int tid512() { int t = threadIdx.x; asm volatile("" : "+v"(t)); return t; }
; DI void gate_reg(PREF p, int l, int n, f32x4 (&acc)[2][2][4][2], int dt) {
;     ...
;         float b[8]; unpack8(bn[m], b);
;         float v[8];
; #pragma unroll
;         for (int nn = 0; nn < 2; ++nn)
; #pragma unroll
;           for (int j = 0; j < 4; ++j) v[nn * 4 + j] = sigm(acc[ai][bj][m][nn][j] + bias[bj][nn]) * b[nn * 4 + j];
;         if (n > 0) {
;           float o[8]; unpack8(pv[m], o);
; #pragma unroll
;           for (int e = 0; e < 8; ++e) v[e] += o[e];
;         }
;         if (n < 3) ssum[((ai * 2 + bj) * 4 + m) * 64] = pack8(v);
; #pragma unroll
;         for (int nn = 0; nn < 2; ++nn)
; #pragma unroll
;           for (int j = 0; j < 4; ++j) acc[ai][bj][m][nn][j] = v[nn * 4 + j];
; template <int AI, int BJ>
; DI void mg_quadrant(PREF p, const f32x4 (&acc)[2][2][4][2], int mt, int dt, float* Cs) {
;   const int t = tid512();
;   const int row0 = mt * 256 + AI * 128, col0 = dt * 256 + BJ * 128;
;   stage_q<AI, BJ>(acc, Cs);
; #pragma unroll
;   for (int q = 0; q < 4; ++q) {
;     int r = (t >> 4) + 32 * q, c = (t & 15) * 8;
;     float v[8]; ld8(Cs + r * CST + c, v);
;     *(u32x4*)(p.mg + (size_t)(row0 + r) * 1024 + col0 + c) = pack8(v);
;   }
	v_fmamk_f32 v54, v54, 0xbfb8aa3b, v170
	v_exp_f32_e32 v54, v54
	v_fmamk_f32 v55, v55, 0xbfb8aa3b, v170
	v_exp_f32_e32 v55, v55
	v_fmamk_f32 v56, v56, 0xbfb8aa3b, v170
	v_exp_f32_e32 v56, v56
	v_fmamk_f32 v57, v57, 0xbfb8aa3b, v170
	v_exp_f32_e32 v57, v57
	v_fmamk_f32 v50, v50, 0xbfb8aa3b, v252
	v_exp_f32_e32 v50, v50
	v_fmamk_f32 v51, v51, 0xbfb8aa3b, v252
	v_exp_f32_e32 v51, v51
	v_fmamk_f32 v52, v52, 0xbfb8aa3b, v252
	v_exp_f32_e32 v52, v52
	v_fmamk_f32 v53, v53, 0xbfb8aa3b, v252
	v_exp_f32_e32 v53, v53
	v_fmamk_f32 v10, v10, 0xbfb8aa3b, v253
	v_exp_f32_e32 v10, v10
	v_fmamk_f32 v11, v11, 0xbfb8aa3b, v253
	v_exp_f32_e32 v11, v11
	v_fmamk_f32 v12, v12, 0xbfb8aa3b, v253
	v_exp_f32_e32 v12, v12
	v_fmamk_f32 v13, v13, 0xbfb8aa3b, v253
	v_exp_f32_e32 v13, v13
	v_fmamk_f32 v2, v2, 0xbfb8aa3b, v162
	v_exp_f32_e32 v2, v2
	v_fmamk_f32 v3, v3, 0xbfb8aa3b, v162
	v_exp_f32_e32 v3, v3
	v_fmamk_f32 v4, v4, 0xbfb8aa3b, v162
	v_exp_f32_e32 v4, v4
	v_fmamk_f32 v5, v5, 0xbfb8aa3b, v162
	v_exp_f32_e32 v5, v5
	v_pk_add_f32 v[54:55], v[54:55], 1.0 op_sel_hi:[1,0]
	v_lshlrev_b32_e32 v156, 16, v190
	v_and_b32_e32 v157, 0xffff0000, v190
	v_rcp_f32_e32 v54, v54
	v_rcp_f32_e32 v55, v55
	v_pk_add_f32 v[56:57], v[56:57], 1.0 op_sel_hi:[1,0]
	v_lshlrev_b32_e32 v164, 16, v191
	v_and_b32_e32 v165, 0xffff0000, v191
	v_rcp_f32_e32 v56, v56
	v_rcp_f32_e32 v57, v57
	v_pk_mul_f32 v[54:55], v[54:55], v[156:157]
	v_pk_mul_f32 v[56:57], v[56:57], v[164:165]
	v_pk_add_f32 v[50:51], v[50:51], 1.0 op_sel_hi:[1,0]
	v_lshlrev_b32_e32 v156, 16, v192
	v_and_b32_e32 v157, 0xffff0000, v192
	v_rcp_f32_e32 v50, v50
	v_rcp_f32_e32 v51, v51
	v_pk_add_f32 v[52:53], v[52:53], 1.0 op_sel_hi:[1,0]
	v_lshlrev_b32_e32 v164, 16, v193
	v_and_b32_e32 v165, 0xffff0000, v193
	v_rcp_f32_e32 v52, v52
	v_rcp_f32_e32 v53, v53
	v_pk_fma_f32 v[54:55], v[50:51], v[156:157], v[54:55]
	v_pk_fma_f32 v[56:57], v[52:53], v[164:165], v[56:57]
	v_pk_add_f32 v[10:11], v[10:11], 1.0 op_sel_hi:[1,0]
	v_lshlrev_b32_e32 v156, 16, v194
	v_and_b32_e32 v157, 0xffff0000, v194
	v_rcp_f32_e32 v10, v10
	v_rcp_f32_e32 v11, v11
	v_pk_add_f32 v[12:13], v[12:13], 1.0 op_sel_hi:[1,0]
	v_lshlrev_b32_e32 v164, 16, v195
	v_and_b32_e32 v165, 0xffff0000, v195
	v_rcp_f32_e32 v12, v12
	v_rcp_f32_e32 v13, v13
	v_pk_fma_f32 v[54:55], v[10:11], v[156:157], v[54:55]
	v_pk_fma_f32 v[56:57], v[12:13], v[164:165], v[56:57]
	v_pk_add_f32 v[2:3], v[2:3], 1.0 op_sel_hi:[1,0]
	v_lshlrev_b32_e32 v156, 16, v196
	v_and_b32_e32 v157, 0xffff0000, v196
	v_rcp_f32_e32 v2, v2
	v_rcp_f32_e32 v3, v3
	v_pk_add_f32 v[4:5], v[4:5], 1.0 op_sel_hi:[1,0]
	v_lshlrev_b32_e32 v164, 16, v197
	v_and_b32_e32 v165, 0xffff0000, v197
	v_rcp_f32_e32 v4, v4
	v_rcp_f32_e32 v5, v5
	v_pk_fma_f32 v[54:55], v[2:3], v[156:157], v[54:55]
	v_pk_fma_f32 v[56:57], v[4:5], v[164:165], v[56:57]
	v_lshrrev_b32_e32 v156, 8, v168
	v_lshlrev_b32_e32 v156, 6, v156
	v_bfe_u32 v157, v168, 4, 2
	v_lshl_add_u32 v156, v157, 2, v156
	v_mul_u32_u24_e32 v156, 0x84, v156
	v_lshlrev_b32_e32 v157, 4, v155
	v_and_b32_e32 v164, 15, v168
	v_add3_u32 v156, v156, v157, v164
	v_lshlrev_b32_e32 v156, 2, v156
	v_lshrrev_b32_e32 v157, 3, v168
	v_lshlrev_b32_e32 v165, 11, v157
	v_mul_u32_u24_e32 v157, 0x84, v157
	v_and_b32_e32 v164, 7, v168
	v_lshl_add_u32 v157, v164, 3, v157
	v_lshlrev_b32_e32 v157, 2, v157
	v_lshl_add_u32 v165, v164, 4, v165
	v_mov_b32_e32 v164, v165
	s_waitcnt lgkmcnt(0)
	s_barrier
	ds_write_b32 v156, v158 offset:0
	ds_write_b32 v156, v159 offset:528
	ds_write_b32 v156, v160 offset:1056
	ds_write_b32 v156, v161 offset:1584
	ds_write_b32 v156, v146 offset:8448
	ds_write_b32 v156, v147 offset:8976
	ds_write_b32 v156, v148 offset:9504
	ds_write_b32 v156, v149 offset:10032
	ds_write_b32 v156, v134 offset:16896
	ds_write_b32 v156, v135 offset:17424
	ds_write_b32 v156, v136 offset:17952
	ds_write_b32 v156, v137 offset:18480
	ds_write_b32 v156, v122 offset:25344
	ds_write_b32 v156, v123 offset:25872
	ds_write_b32 v156, v124 offset:26400
	ds_write_b32 v156, v125 offset:26928
	s_waitcnt lgkmcnt(0)
	s_barrier
	s_add_i32 s0, s12, 0
	s_lshl_b32 s0, s0, 11
	s_lshl_b32 s1, s23, 7
	s_add_u32 s0, s0, s1
	s_add_u32 s0, s36, s0
	s_addc_u32 s1, s37, 0
	ds_read_b128 v[230:233], v157 offset:0
	ds_read_b128 v[234:237], v157 offset:16
	ds_read_b128 v[238:241], v157 offset:33792
	ds_read_b128 v[242:245], v157 offset:33808
	s_waitcnt lgkmcnt(2)
	v_cvt_pk_bf16_f32 v230, v230, v231
	v_cvt_pk_bf16_f32 v231, v232, v233
	v_cvt_pk_bf16_f32 v232, v234, v235
	v_cvt_pk_bf16_f32 v233, v236, v237
	global_store_dwordx4 v164, v[230:233], s[0:1]
	s_waitcnt lgkmcnt(0)
	v_cvt_pk_bf16_f32 v238, v238, v239
	v_cvt_pk_bf16_f32 v239, v240, v241
	v_cvt_pk_bf16_f32 v240, v242, v243
	v_cvt_pk_bf16_f32 v241, v244, v245
	v_add_u32_e32 v164, 0x20000, v164
	global_store_dwordx4 v164, v[238:241], s[0:1]
	v_mov_b32_e32 v164, v165
	s_waitcnt lgkmcnt(0)
	s_barrier
	ds_write_b32 v156, v78 offset:0
	ds_write_b32 v156, v79 offset:528
	ds_write_b32 v156, v80 offset:1056
	ds_write_b32 v156, v81 offset:1584
	ds_write_b32 v156, v70 offset:8448
	ds_write_b32 v156, v71 offset:8976
	ds_write_b32 v156, v72 offset:9504
	ds_write_b32 v156, v73 offset:10032
	ds_write_b32 v156, v62 offset:16896
	ds_write_b32 v156, v63 offset:17424
	ds_write_b32 v156, v64 offset:17952
	ds_write_b32 v156, v65 offset:18480
	ds_write_b32 v156, v54 offset:25344
	ds_write_b32 v156, v55 offset:25872
	ds_write_b32 v156, v56 offset:26400
	ds_write_b32 v156, v57 offset:26928
	s_waitcnt lgkmcnt(0)
	s_barrier
	s_add_i32 s0, s12, 128
	s_lshl_b32 s0, s0, 11
	s_lshl_b32 s1, s23, 7
	s_add_u32 s0, s0, s1
	s_add_u32 s0, s36, s0
	s_addc_u32 s1, s37, 0
	ds_read_b128 v[230:233], v157 offset:0
	ds_read_b128 v[234:237], v157 offset:16
	ds_read_b128 v[238:241], v157 offset:33792
	ds_read_b128 v[242:245], v157 offset:33808
	s_waitcnt lgkmcnt(2)
	v_cvt_pk_bf16_f32 v230, v230, v231
	v_cvt_pk_bf16_f32 v231, v232, v233
	v_cvt_pk_bf16_f32 v232, v234, v235
	v_cvt_pk_bf16_f32 v233, v236, v237
	global_store_dwordx4 v164, v[230:233], s[0:1]
	s_waitcnt lgkmcnt(0)
	v_cvt_pk_bf16_f32 v238, v238, v239
	v_cvt_pk_bf16_f32 v239, v240, v241
	v_cvt_pk_bf16_f32 v240, v242, v243
	v_cvt_pk_bf16_f32 v241, v244, v245
	v_add_u32_e32 v164, 0x20000, v164
	global_store_dwordx4 v164, v[238:241], s[0:1]
	s_branch .LBB0_101
